# ODD_IN GEMM converted to the LDS-DMA BK=64 core (B operand base from v255 lanes 22/23)
# speedup vs baseline: 1.0067x; 1.0066x over previous
.LBB0_164:
	s_and_b32 s0, s81, 0xff
	s_mulk_i32 s0, 0xcd
	s_lshr_b32 s1, s0, 11
	s_and_b32 s0, s0, 0xf800
	s_waitcnt vmcnt(0)
	s_or_b32 s10, s0, s75
	s_mul_i32 s1, s1, 10
	s_sub_i32 s0, s81, s1
	s_and_b32 s9, s0, 0xff
	s_lshl_b32 s8, s9, 7
	s_mov_b32 s13, 0
	s_mov_b64 s[0:1], s[86:87]
	v_readlane_b32 s42, v255, 22
	v_readlane_b32 s43, v255, 23
	s_nop 0
	s_lshr_b32 s21, s10, 21
	s_lshl_b32 s20, s10, 11
	s_add_u32 s50, s70, s20
	s_addc_u32 s51, s71, s21
	s_add_u32 s52, s50, 0x8000
	s_addc_u32 s53, s51, 0
	s_add_u32 s54, s52, 0x8000
	s_addc_u32 s55, s53, 0
	s_add_u32 s56, s54, 0x8000
	s_addc_u32 s57, s55, 0
	s_lshr_b32 s21, s8, 21
	s_lshl_b32 s20, s8, 11
	s_add_u32 s58, s42, s20
	s_addc_u32 s59, s43, s21
	s_add_u32 s60, s58, 0x8000
	s_addc_u32 s61, s59, 0
	v_lshrrev_b32_e32 v246, 6, v179
	s_nop 0
	v_readfirstlane_b32 s63, v246
	v_and_b32_e32 v247, 63, v179
	v_lshrrev_b32_e32 v248, 3, v247
	v_and_b32_e32 v249, 7, v247
	v_lshrrev_b32_e32 v246, 1, v248
	v_lshrrev_b32_e32 v247, 2, v248
	v_xor_b32_e32 v0, v246, v247
	v_xor_b32_e32 v130, 5, v0
	v_xor_b32_e32 v0, v0, v249
	v_lshlrev_b32_e32 v0, 4, v0
	v_mov_b32_e32 v131, v0
	v_xor_b32_e32 v130, v130, v249
	v_lshlrev_b32_e32 v130, 4, v130
	v_mov_b32_e32 v132, v130
	s_lshl_b32 s41, s63, 6
	v_add_u32_e32 v246, s41, v248
	v_lshl_add_u32 v0, v246, 11, v0
	v_add_u32_e32 v246, 8, v246
	v_lshl_add_u32 v130, v246, 11, v130
	s_lshl_b32 s41, s63, 5
	v_add_u32_e32 v246, s41, v248
	v_lshl_add_u32 v131, v246, 11, v131
	v_add_u32_e32 v246, 8, v246
	v_lshl_add_u32 v132, v246, 11, v132
	v_and_b32_e32 v246, 15, v179
	v_bfe_u32 v247, v179, 4, 2
	v_lshrrev_b32_e32 v248, 1, v246
	v_add_u32_e32 v249, 4, v246
	v_bfe_u32 v249, v249, 3, 1
	v_xor_b32_e32 v248, v248, v249
	v_xor_b32_e32 v247, v247, v248
	v_lshlrev_b32_e32 v247, 4, v247
	v_lshl_add_u32 v159, v246, 7, v247
	s_lshl_b32 s41, s63, 13
	v_add_u32_e32 v137, s41, v159
	v_add_u32_e32 v159, 32768, v159
	v_xor_b32_e32 v158, 64, v137
	v_xor_b32_e32 v160, 64, v159
	s_lshl_b32 s46, s63, 13
	s_lshl_b32 s47, s63, 12
	s_add_u32 s47, s47, 32768
	v_mov_b32_e32 v126, 0
	v_mov_b32_e32 v127, 0
	v_mov_b32_e32 v128, 0
	v_mov_b32_e32 v129, 0
	v_mov_b32_e32 v122, 0
	v_mov_b32_e32 v123, 0
	v_mov_b32_e32 v124, 0
	v_mov_b32_e32 v125, 0
	v_mov_b32_e32 v118, 0
	v_mov_b32_e32 v119, 0
	v_mov_b32_e32 v120, 0
	v_mov_b32_e32 v121, 0
	v_mov_b32_e32 v114, 0
	v_mov_b32_e32 v115, 0
	v_mov_b32_e32 v116, 0
	v_mov_b32_e32 v117, 0
	v_mov_b32_e32 v110, 0
	v_mov_b32_e32 v111, 0
	v_mov_b32_e32 v112, 0
	v_mov_b32_e32 v113, 0
	v_mov_b32_e32 v106, 0
	v_mov_b32_e32 v107, 0
	v_mov_b32_e32 v108, 0
	v_mov_b32_e32 v109, 0
	v_mov_b32_e32 v102, 0
	v_mov_b32_e32 v103, 0
	v_mov_b32_e32 v104, 0
	v_mov_b32_e32 v105, 0
	v_mov_b32_e32 v98, 0
	v_mov_b32_e32 v99, 0
	v_mov_b32_e32 v100, 0
	v_mov_b32_e32 v101, 0
	v_mov_b32_e32 v94, 0
	v_mov_b32_e32 v95, 0
	v_mov_b32_e32 v96, 0
	v_mov_b32_e32 v97, 0
	v_mov_b32_e32 v90, 0
	v_mov_b32_e32 v91, 0
	v_mov_b32_e32 v92, 0
	v_mov_b32_e32 v93, 0
	v_mov_b32_e32 v86, 0
	v_mov_b32_e32 v87, 0
	v_mov_b32_e32 v88, 0
	v_mov_b32_e32 v89, 0
	v_mov_b32_e32 v82, 0
	v_mov_b32_e32 v83, 0
	v_mov_b32_e32 v84, 0
	v_mov_b32_e32 v85, 0
	v_mov_b32_e32 v78, 0
	v_mov_b32_e32 v79, 0
	v_mov_b32_e32 v80, 0
	v_mov_b32_e32 v81, 0
	v_mov_b32_e32 v74, 0
	v_mov_b32_e32 v75, 0
	v_mov_b32_e32 v76, 0
	v_mov_b32_e32 v77, 0
	v_mov_b32_e32 v70, 0
	v_mov_b32_e32 v71, 0
	v_mov_b32_e32 v72, 0
	v_mov_b32_e32 v73, 0
	v_mov_b32_e32 v66, 0
	v_mov_b32_e32 v67, 0
	v_mov_b32_e32 v68, 0
	v_mov_b32_e32 v69, 0
	v_mov_b32_e32 v62, 0
	v_mov_b32_e32 v63, 0
	v_mov_b32_e32 v64, 0
	v_mov_b32_e32 v65, 0
	v_mov_b32_e32 v58, 0
	v_mov_b32_e32 v59, 0
	v_mov_b32_e32 v60, 0
	v_mov_b32_e32 v61, 0
	v_mov_b32_e32 v54, 0
	v_mov_b32_e32 v55, 0
	v_mov_b32_e32 v56, 0
	v_mov_b32_e32 v57, 0
	v_mov_b32_e32 v50, 0
	v_mov_b32_e32 v51, 0
	v_mov_b32_e32 v52, 0
	v_mov_b32_e32 v53, 0
	v_mov_b32_e32 v46, 0
	v_mov_b32_e32 v47, 0
	v_mov_b32_e32 v48, 0
	v_mov_b32_e32 v49, 0
	v_mov_b32_e32 v42, 0
	v_mov_b32_e32 v43, 0
	v_mov_b32_e32 v44, 0
	v_mov_b32_e32 v45, 0
	v_mov_b32_e32 v38, 0
	v_mov_b32_e32 v39, 0
	v_mov_b32_e32 v40, 0
	v_mov_b32_e32 v41, 0
	v_mov_b32_e32 v34, 0
	v_mov_b32_e32 v35, 0
	v_mov_b32_e32 v36, 0
	v_mov_b32_e32 v37, 0
	v_mov_b32_e32 v30, 0
	v_mov_b32_e32 v31, 0
	v_mov_b32_e32 v32, 0
	v_mov_b32_e32 v33, 0
	v_mov_b32_e32 v26, 0
	v_mov_b32_e32 v27, 0
	v_mov_b32_e32 v28, 0
	v_mov_b32_e32 v29, 0
	v_mov_b32_e32 v22, 0
	v_mov_b32_e32 v23, 0
	v_mov_b32_e32 v24, 0
	v_mov_b32_e32 v25, 0
	v_mov_b32_e32 v18, 0
	v_mov_b32_e32 v19, 0
	v_mov_b32_e32 v20, 0
	v_mov_b32_e32 v21, 0
	v_mov_b32_e32 v14, 0
	v_mov_b32_e32 v15, 0
	v_mov_b32_e32 v16, 0
	v_mov_b32_e32 v17, 0
	v_mov_b32_e32 v10, 0
	v_mov_b32_e32 v11, 0
	v_mov_b32_e32 v12, 0
	v_mov_b32_e32 v13, 0
	v_mov_b32_e32 v6, 0
	v_mov_b32_e32 v7, 0
	v_mov_b32_e32 v8, 0
	v_mov_b32_e32 v9, 0
	v_mov_b32_e32 v2, 0
	v_mov_b32_e32 v3, 0
	v_mov_b32_e32 v4, 0
	v_mov_b32_e32 v5, 0
	s_barrier
	s_mov_b32 m0, s46
	s_nop 0
	global_load_lds_dwordx4 v0, s[50:51]
	s_add_u32 m0, s46, 1024
	s_nop 0
	global_load_lds_dwordx4 v130, s[50:51]
	s_add_u32 m0, s46, 2048
	s_nop 0
	global_load_lds_dwordx4 v0, s[52:53]
	s_add_u32 m0, s46, 3072
	s_nop 0
	global_load_lds_dwordx4 v130, s[52:53]
	s_add_u32 m0, s46, 4096
	s_nop 0
	global_load_lds_dwordx4 v0, s[54:55]
	s_add_u32 m0, s46, 5120
	s_nop 0
	global_load_lds_dwordx4 v130, s[54:55]
	s_add_u32 m0, s46, 6144
	s_nop 0
	global_load_lds_dwordx4 v0, s[56:57]
	s_add_u32 m0, s46, 7168
	s_nop 0
	global_load_lds_dwordx4 v130, s[56:57]
	s_mov_b32 m0, s47
	s_nop 0
	global_load_lds_dwordx4 v131, s[58:59]
	s_add_u32 m0, s47, 1024
	s_nop 0
	global_load_lds_dwordx4 v132, s[58:59]
	s_add_u32 m0, s47, 2048
	s_nop 0
	global_load_lds_dwordx4 v131, s[60:61]
	s_add_u32 m0, s47, 3072
	s_nop 0
	global_load_lds_dwordx4 v132, s[60:61]
	s_add_u32 s50, s50, 0x80
	s_addc_u32 s51, s51, 0
	s_add_u32 s52, s52, 0x80
	s_addc_u32 s53, s53, 0
	s_add_u32 s54, s54, 0x80
	s_addc_u32 s55, s55, 0
	s_add_u32 s56, s56, 0x80
	s_addc_u32 s57, s57, 0
	s_add_u32 s58, s58, 0x80
	s_addc_u32 s59, s59, 0
	s_add_u32 s60, s60, 0x80
	s_addc_u32 s61, s61, 0
	s_mov_b32 s49, 15
.Lg3_oin_loop:
	s_waitcnt vmcnt(0)
	ds_read_b128 v[226:229], v137
	ds_read_b128 v[230:233], v137 offset:2048
	ds_read_b128 v[234:237], v137 offset:4096
	ds_read_b128 v[238:241], v137 offset:6144
	ds_read_b128 v[242:245], v158
	ds_read_b128 v[246:249], v158 offset:2048
	s_barrier
	ds_read_b128 v[138:141], v159
	ds_read_b128 v[142:145], v159 offset:2048
	ds_read_b128 v[146:149], v159 offset:4096
	ds_read_b128 v[150:153], v159 offset:6144
	ds_read_b128 v[154:157], v159 offset:8192
	ds_read_b128 v[162:165], v159 offset:10240
	ds_read_b128 v[166:169], v159 offset:12288
	ds_read_b128 v[170:173], v159 offset:14336
	s_waitcnt lgkmcnt(7)
	v_mfma_f32_16x16x32_bf16 v[126:129], v[138:141], v[226:229], v[126:129]
	v_mfma_f32_16x16x32_bf16 v[94:97], v[138:141], v[230:233], v[94:97]
	v_mfma_f32_16x16x32_bf16 v[62:65], v[138:141], v[234:237], v[62:65]
	v_mfma_f32_16x16x32_bf16 v[30:33], v[138:141], v[238:241], v[30:33]
	s_waitcnt lgkmcnt(6)
	v_mfma_f32_16x16x32_bf16 v[122:125], v[142:145], v[226:229], v[122:125]
	v_mfma_f32_16x16x32_bf16 v[90:93], v[142:145], v[230:233], v[90:93]
	v_mfma_f32_16x16x32_bf16 v[58:61], v[142:145], v[234:237], v[58:61]
	v_mfma_f32_16x16x32_bf16 v[26:29], v[142:145], v[238:241], v[26:29]
	ds_read_b128 v[142:145], v158 offset:4096
	ds_read_b128 v[138:141], v158 offset:6144
	ds_read_b128 v[174:177], v160
	ds_read_b128 v[180:183], v160 offset:2048
	ds_read_b128 v[186:189], v160 offset:4096
	ds_read_b128 v[194:197], v160 offset:6144
	ds_read_b128 v[198:201], v160 offset:8192
	ds_read_b128 v[202:205], v160 offset:10240
	ds_read_b128 v[206:209], v160 offset:12288
	ds_read_b128 v[216:219], v160 offset:14336
	s_waitcnt lgkmcnt(8)
	s_mov_b32 m0, s46
	s_nop 0
	global_load_lds_dwordx4 v0, s[50:51]
	s_add_u32 m0, s46, 1024
	s_nop 0
	global_load_lds_dwordx4 v130, s[50:51]
	s_add_u32 m0, s46, 2048
	s_nop 0
	global_load_lds_dwordx4 v0, s[52:53]
	s_add_u32 m0, s46, 3072
	s_nop 0
	global_load_lds_dwordx4 v130, s[52:53]
	s_add_u32 m0, s46, 4096
	s_nop 0
	global_load_lds_dwordx4 v0, s[54:55]
	s_add_u32 m0, s46, 5120
	s_nop 0
	global_load_lds_dwordx4 v130, s[54:55]
	s_add_u32 m0, s46, 6144
	s_nop 0
	global_load_lds_dwordx4 v0, s[56:57]
	s_add_u32 m0, s46, 7168
	s_nop 0
	global_load_lds_dwordx4 v130, s[56:57]
	s_add_u32 s50, s50, 0x80
	s_addc_u32 s51, s51, 0
	s_add_u32 s52, s52, 0x80
	s_addc_u32 s53, s53, 0
	s_add_u32 s54, s54, 0x80
	s_addc_u32 s55, s55, 0
	s_add_u32 s56, s56, 0x80
	s_addc_u32 s57, s57, 0
	s_waitcnt lgkmcnt(0)
	s_barrier
	s_mov_b32 m0, s47
	s_nop 0
	global_load_lds_dwordx4 v131, s[58:59]
	s_add_u32 m0, s47, 1024
	s_nop 0
	global_load_lds_dwordx4 v132, s[58:59]
	s_add_u32 m0, s47, 2048
	s_nop 0
	global_load_lds_dwordx4 v131, s[60:61]
	s_add_u32 m0, s47, 3072
	s_nop 0
	global_load_lds_dwordx4 v132, s[60:61]
	s_add_u32 s58, s58, 0x80
	s_addc_u32 s59, s59, 0
	s_add_u32 s60, s60, 0x80
	s_addc_u32 s61, s61, 0
	v_mfma_f32_16x16x32_bf16 v[118:121], v[146:149], v[226:229], v[118:121]
	v_mfma_f32_16x16x32_bf16 v[86:89], v[146:149], v[230:233], v[86:89]
	v_mfma_f32_16x16x32_bf16 v[54:57], v[146:149], v[234:237], v[54:57]
	v_mfma_f32_16x16x32_bf16 v[22:25], v[146:149], v[238:241], v[22:25]
	v_mfma_f32_16x16x32_bf16 v[114:117], v[150:153], v[226:229], v[114:117]
	v_mfma_f32_16x16x32_bf16 v[82:85], v[150:153], v[230:233], v[82:85]
	v_mfma_f32_16x16x32_bf16 v[50:53], v[150:153], v[234:237], v[50:53]
	v_mfma_f32_16x16x32_bf16 v[18:21], v[150:153], v[238:241], v[18:21]
	v_mfma_f32_16x16x32_bf16 v[110:113], v[154:157], v[226:229], v[110:113]
	v_mfma_f32_16x16x32_bf16 v[78:81], v[154:157], v[230:233], v[78:81]
	v_mfma_f32_16x16x32_bf16 v[46:49], v[154:157], v[234:237], v[46:49]
	v_mfma_f32_16x16x32_bf16 v[14:17], v[154:157], v[238:241], v[14:17]
	v_mfma_f32_16x16x32_bf16 v[106:109], v[162:165], v[226:229], v[106:109]
	v_mfma_f32_16x16x32_bf16 v[74:77], v[162:165], v[230:233], v[74:77]
	v_mfma_f32_16x16x32_bf16 v[42:45], v[162:165], v[234:237], v[42:45]
	v_mfma_f32_16x16x32_bf16 v[10:13], v[162:165], v[238:241], v[10:13]
	v_mfma_f32_16x16x32_bf16 v[102:105], v[166:169], v[226:229], v[102:105]
	v_mfma_f32_16x16x32_bf16 v[70:73], v[166:169], v[230:233], v[70:73]
	v_mfma_f32_16x16x32_bf16 v[38:41], v[166:169], v[234:237], v[38:41]
	v_mfma_f32_16x16x32_bf16 v[6:9], v[166:169], v[238:241], v[6:9]
	v_mfma_f32_16x16x32_bf16 v[98:101], v[170:173], v[226:229], v[98:101]
	v_mfma_f32_16x16x32_bf16 v[66:69], v[170:173], v[230:233], v[66:69]
	v_mfma_f32_16x16x32_bf16 v[34:37], v[170:173], v[234:237], v[34:37]
	v_mfma_f32_16x16x32_bf16 v[2:5], v[170:173], v[238:241], v[2:5]
	v_mfma_f32_16x16x32_bf16 v[126:129], v[174:177], v[242:245], v[126:129]
	v_mfma_f32_16x16x32_bf16 v[94:97], v[174:177], v[246:249], v[94:97]
	v_mfma_f32_16x16x32_bf16 v[62:65], v[174:177], v[142:145], v[62:65]
	v_mfma_f32_16x16x32_bf16 v[30:33], v[174:177], v[138:141], v[30:33]
	v_mfma_f32_16x16x32_bf16 v[122:125], v[180:183], v[242:245], v[122:125]
	v_mfma_f32_16x16x32_bf16 v[90:93], v[180:183], v[246:249], v[90:93]
	v_mfma_f32_16x16x32_bf16 v[58:61], v[180:183], v[142:145], v[58:61]
	v_mfma_f32_16x16x32_bf16 v[26:29], v[180:183], v[138:141], v[26:29]
	v_mfma_f32_16x16x32_bf16 v[118:121], v[186:189], v[242:245], v[118:121]
	v_mfma_f32_16x16x32_bf16 v[86:89], v[186:189], v[246:249], v[86:89]
	v_mfma_f32_16x16x32_bf16 v[54:57], v[186:189], v[142:145], v[54:57]
	v_mfma_f32_16x16x32_bf16 v[22:25], v[186:189], v[138:141], v[22:25]
	v_mfma_f32_16x16x32_bf16 v[114:117], v[194:197], v[242:245], v[114:117]
	v_mfma_f32_16x16x32_bf16 v[82:85], v[194:197], v[246:249], v[82:85]
	v_mfma_f32_16x16x32_bf16 v[50:53], v[194:197], v[142:145], v[50:53]
	v_mfma_f32_16x16x32_bf16 v[18:21], v[194:197], v[138:141], v[18:21]
	v_mfma_f32_16x16x32_bf16 v[110:113], v[198:201], v[242:245], v[110:113]
	v_mfma_f32_16x16x32_bf16 v[78:81], v[198:201], v[246:249], v[78:81]
	v_mfma_f32_16x16x32_bf16 v[46:49], v[198:201], v[142:145], v[46:49]
	v_mfma_f32_16x16x32_bf16 v[14:17], v[198:201], v[138:141], v[14:17]
	v_mfma_f32_16x16x32_bf16 v[106:109], v[202:205], v[242:245], v[106:109]
	v_mfma_f32_16x16x32_bf16 v[74:77], v[202:205], v[246:249], v[74:77]
	v_mfma_f32_16x16x32_bf16 v[42:45], v[202:205], v[142:145], v[42:45]
	v_mfma_f32_16x16x32_bf16 v[10:13], v[202:205], v[138:141], v[10:13]
	v_mfma_f32_16x16x32_bf16 v[102:105], v[206:209], v[242:245], v[102:105]
	v_mfma_f32_16x16x32_bf16 v[70:73], v[206:209], v[246:249], v[70:73]
	v_mfma_f32_16x16x32_bf16 v[38:41], v[206:209], v[142:145], v[38:41]
	v_mfma_f32_16x16x32_bf16 v[6:9], v[206:209], v[138:141], v[6:9]
	v_mfma_f32_16x16x32_bf16 v[98:101], v[216:219], v[242:245], v[98:101]
	v_mfma_f32_16x16x32_bf16 v[66:69], v[216:219], v[246:249], v[66:69]
	v_mfma_f32_16x16x32_bf16 v[34:37], v[216:219], v[142:145], v[34:37]
	v_mfma_f32_16x16x32_bf16 v[2:5], v[216:219], v[138:141], v[2:5]
	s_sub_u32 s49, s49, 1
	s_cmp_lg_u32 s49, 0
	s_cbranch_scc1 .Lg3_oin_loop
	s_waitcnt vmcnt(0)
	ds_read_b128 v[226:229], v137
	ds_read_b128 v[230:233], v137 offset:2048
	ds_read_b128 v[234:237], v137 offset:4096
	ds_read_b128 v[238:241], v137 offset:6144
	ds_read_b128 v[242:245], v158
	ds_read_b128 v[246:249], v158 offset:2048
	s_barrier
	ds_read_b128 v[138:141], v159
	ds_read_b128 v[142:145], v159 offset:2048
	ds_read_b128 v[146:149], v159 offset:4096
	ds_read_b128 v[150:153], v159 offset:6144
	ds_read_b128 v[154:157], v159 offset:8192
	ds_read_b128 v[162:165], v159 offset:10240
	ds_read_b128 v[166:169], v159 offset:12288
	ds_read_b128 v[170:173], v159 offset:14336
	s_waitcnt lgkmcnt(7)
	v_mfma_f32_16x16x32_bf16 v[126:129], v[138:141], v[226:229], v[126:129]
	v_mfma_f32_16x16x32_bf16 v[94:97], v[138:141], v[230:233], v[94:97]
	v_mfma_f32_16x16x32_bf16 v[62:65], v[138:141], v[234:237], v[62:65]
	v_mfma_f32_16x16x32_bf16 v[30:33], v[138:141], v[238:241], v[30:33]
	s_waitcnt lgkmcnt(6)
	v_mfma_f32_16x16x32_bf16 v[122:125], v[142:145], v[226:229], v[122:125]
	v_mfma_f32_16x16x32_bf16 v[90:93], v[142:145], v[230:233], v[90:93]
	v_mfma_f32_16x16x32_bf16 v[58:61], v[142:145], v[234:237], v[58:61]
	v_mfma_f32_16x16x32_bf16 v[26:29], v[142:145], v[238:241], v[26:29]
	ds_read_b128 v[142:145], v158 offset:4096
	ds_read_b128 v[138:141], v158 offset:6144
	ds_read_b128 v[174:177], v160
	ds_read_b128 v[180:183], v160 offset:2048
	ds_read_b128 v[186:189], v160 offset:4096
	ds_read_b128 v[194:197], v160 offset:6144
	ds_read_b128 v[198:201], v160 offset:8192
	ds_read_b128 v[202:205], v160 offset:10240
	ds_read_b128 v[206:209], v160 offset:12288
	ds_read_b128 v[216:219], v160 offset:14336
	s_waitcnt lgkmcnt(8)
	s_waitcnt lgkmcnt(0)
	s_barrier
	v_mfma_f32_16x16x32_bf16 v[118:121], v[146:149], v[226:229], v[118:121]
	v_mfma_f32_16x16x32_bf16 v[86:89], v[146:149], v[230:233], v[86:89]
	v_mfma_f32_16x16x32_bf16 v[54:57], v[146:149], v[234:237], v[54:57]
	v_mfma_f32_16x16x32_bf16 v[22:25], v[146:149], v[238:241], v[22:25]
	v_mfma_f32_16x16x32_bf16 v[114:117], v[150:153], v[226:229], v[114:117]
	v_mfma_f32_16x16x32_bf16 v[82:85], v[150:153], v[230:233], v[82:85]
	v_mfma_f32_16x16x32_bf16 v[50:53], v[150:153], v[234:237], v[50:53]
	v_mfma_f32_16x16x32_bf16 v[18:21], v[150:153], v[238:241], v[18:21]
	v_mfma_f32_16x16x32_bf16 v[110:113], v[154:157], v[226:229], v[110:113]
	v_mfma_f32_16x16x32_bf16 v[78:81], v[154:157], v[230:233], v[78:81]
	v_mfma_f32_16x16x32_bf16 v[46:49], v[154:157], v[234:237], v[46:49]
	v_mfma_f32_16x16x32_bf16 v[14:17], v[154:157], v[238:241], v[14:17]
	v_mfma_f32_16x16x32_bf16 v[106:109], v[162:165], v[226:229], v[106:109]
	v_mfma_f32_16x16x32_bf16 v[74:77], v[162:165], v[230:233], v[74:77]
	v_mfma_f32_16x16x32_bf16 v[42:45], v[162:165], v[234:237], v[42:45]
	v_mfma_f32_16x16x32_bf16 v[10:13], v[162:165], v[238:241], v[10:13]
	v_mfma_f32_16x16x32_bf16 v[102:105], v[166:169], v[226:229], v[102:105]
	v_mfma_f32_16x16x32_bf16 v[70:73], v[166:169], v[230:233], v[70:73]
	v_mfma_f32_16x16x32_bf16 v[38:41], v[166:169], v[234:237], v[38:41]
	v_mfma_f32_16x16x32_bf16 v[6:9], v[166:169], v[238:241], v[6:9]
	v_mfma_f32_16x16x32_bf16 v[98:101], v[170:173], v[226:229], v[98:101]
	v_mfma_f32_16x16x32_bf16 v[66:69], v[170:173], v[230:233], v[66:69]
	v_mfma_f32_16x16x32_bf16 v[34:37], v[170:173], v[234:237], v[34:37]
	v_mfma_f32_16x16x32_bf16 v[2:5], v[170:173], v[238:241], v[2:5]
	v_mfma_f32_16x16x32_bf16 v[126:129], v[174:177], v[242:245], v[126:129]
	v_mfma_f32_16x16x32_bf16 v[94:97], v[174:177], v[246:249], v[94:97]
	v_mfma_f32_16x16x32_bf16 v[62:65], v[174:177], v[142:145], v[62:65]
	v_mfma_f32_16x16x32_bf16 v[30:33], v[174:177], v[138:141], v[30:33]
	v_mfma_f32_16x16x32_bf16 v[122:125], v[180:183], v[242:245], v[122:125]
	v_mfma_f32_16x16x32_bf16 v[90:93], v[180:183], v[246:249], v[90:93]
	v_mfma_f32_16x16x32_bf16 v[58:61], v[180:183], v[142:145], v[58:61]
	v_mfma_f32_16x16x32_bf16 v[26:29], v[180:183], v[138:141], v[26:29]
	v_mfma_f32_16x16x32_bf16 v[118:121], v[186:189], v[242:245], v[118:121]
	v_mfma_f32_16x16x32_bf16 v[86:89], v[186:189], v[246:249], v[86:89]
	v_mfma_f32_16x16x32_bf16 v[54:57], v[186:189], v[142:145], v[54:57]
	v_mfma_f32_16x16x32_bf16 v[22:25], v[186:189], v[138:141], v[22:25]
	v_mfma_f32_16x16x32_bf16 v[114:117], v[194:197], v[242:245], v[114:117]
	v_mfma_f32_16x16x32_bf16 v[82:85], v[194:197], v[246:249], v[82:85]
	v_mfma_f32_16x16x32_bf16 v[50:53], v[194:197], v[142:145], v[50:53]
	v_mfma_f32_16x16x32_bf16 v[18:21], v[194:197], v[138:141], v[18:21]
	v_mfma_f32_16x16x32_bf16 v[110:113], v[198:201], v[242:245], v[110:113]
	v_mfma_f32_16x16x32_bf16 v[78:81], v[198:201], v[246:249], v[78:81]
	v_mfma_f32_16x16x32_bf16 v[46:49], v[198:201], v[142:145], v[46:49]
	v_mfma_f32_16x16x32_bf16 v[14:17], v[198:201], v[138:141], v[14:17]
	v_mfma_f32_16x16x32_bf16 v[106:109], v[202:205], v[242:245], v[106:109]
	v_mfma_f32_16x16x32_bf16 v[74:77], v[202:205], v[246:249], v[74:77]
	v_mfma_f32_16x16x32_bf16 v[42:45], v[202:205], v[142:145], v[42:45]
	v_mfma_f32_16x16x32_bf16 v[10:13], v[202:205], v[138:141], v[10:13]
	v_mfma_f32_16x16x32_bf16 v[102:105], v[206:209], v[242:245], v[102:105]
	v_mfma_f32_16x16x32_bf16 v[70:73], v[206:209], v[246:249], v[70:73]
	v_mfma_f32_16x16x32_bf16 v[38:41], v[206:209], v[142:145], v[38:41]
	v_mfma_f32_16x16x32_bf16 v[6:9], v[206:209], v[138:141], v[6:9]
	v_mfma_f32_16x16x32_bf16 v[98:101], v[216:219], v[242:245], v[98:101]
	v_mfma_f32_16x16x32_bf16 v[66:69], v[216:219], v[246:249], v[66:69]
	v_mfma_f32_16x16x32_bf16 v[34:37], v[216:219], v[142:145], v[34:37]
	v_mfma_f32_16x16x32_bf16 v[2:5], v[216:219], v[138:141], v[2:5]
	s_branch .LBB0_168
